# NORM / FINAL row reductions on the VALU (DPP quad_perm / row mirrors + permlane16/32 swaps) instead of 6 serialized LDS swizzle round trips each; bit-identical sums
# speedup vs baseline: 1.0102x; 1.0102x over previous
; template <int X> __device__ __forceinline__ float swz_xor(float v) { return __int_as_float(__builtin_amdgcn_ds_swizzle(__float_as_int(v), 0x1f | (X << 10))); }
; __device__ __forceinline__ float xor32(float v, int x32a) { return __int_as_float(__builtin_amdgcn_ds_bpermute(x32a, __float_as_int(v))); }
; __device__ __forceinline__ float wave_sum(float v, int x32a) {
;     v += swz_xor<1>(v); v += swz_xor<2>(v); v += swz_xor<4>(v); v += swz_xor<8>(v); v += swz_xor<16>(v); v += xor32(v, x32a);
;     return v;
; __device__ __forceinline__ void final_phase(const Params& p) {
;     ...
;         for (int rr = 0; rr < RPW; rr += 2) {
;             f32x4* xa = (f32x4*)(p.out + (size_t)(r0 + rr) * DM) + lane; f32x4* xb = xa + DM / 4;
;             f32x4 va[4], vb[4]; float sa = 0.f, sb = 0.f;
; #pragma unroll
;             for (int j = 0; j < 4; ++j) { va[j] = __builtin_nontemporal_load(xa + 64 * j); vb[j] = __builtin_nontemporal_load(xb + 64 * j); }
; #pragma unroll
;             for (int j = 0; j < 4; ++j) { sa += (va[j][0] * va[j][0] + va[j][1] * va[j][1]) + (va[j][2] * va[j][2] + va[j][3] * va[j][3]); sb += (vb[j][0] * vb[j][0] + vb[j][1] * vb[j][1]) + (vb[j][2] * vb[j][2] + vb[j][3] * vb[j][3]); }
;             const float ra = rsqrtf(wave_sum(sa, x32a) * (1.0f / DM) + 1e-6f), rb = rsqrtf(wave_sum(sb, x32a) * (1.0f / DM) + 1e-6f);
; #pragma unroll
;             for (int j = 0; j < 4; ++j) { xa[64 * j] = (va[j] * ra) * gg[j]; xb[64 * j] = (vb[j] * rb) * gg[j]; }
.LBB0_30:
	global_load_dwordx4 v[46:49], v[54:55], off offset:-4096 nt
	global_load_dwordx4 v[42:45], v[54:55], off nt
	global_load_dwordx4 v[38:41], v[54:55], off offset:-3072 nt
	global_load_dwordx4 v[34:37], v[54:55], off offset:1024 nt
	global_load_dwordx4 v[30:33], v[54:55], off offset:-2048 nt
	global_load_dwordx4 v[26:29], v[54:55], off offset:2048 nt
	global_load_dwordx4 v[22:25], v[54:55], off offset:-1024 nt
	global_load_dwordx4 v[18:21], v[54:55], off offset:3072 nt
	v_lshl_add_u64 v[102:103], v[54:55], 0, s[6:7]
	global_load_dwordx4 v[70:73], v[102:103], off offset:-4096 nt
	global_load_dwordx4 v[74:77], v[102:103], off nt
	global_load_dwordx4 v[78:81], v[102:103], off offset:-3072 nt
	global_load_dwordx4 v[82:85], v[102:103], off offset:1024 nt
	global_load_dwordx4 v[86:89], v[102:103], off offset:-2048 nt
	global_load_dwordx4 v[90:93], v[102:103], off offset:2048 nt
	global_load_dwordx4 v[94:97], v[102:103], off offset:-1024 nt
	global_load_dwordx4 v[98:101], v[102:103], off offset:3072 nt
	s_add_i32 s4, s4, 2
	s_cmp_gt_u32 s4, 13
	s_waitcnt vmcnt(8)
	v_pk_mul_f32 v[56:57], v[48:49], v[48:49]
	v_pk_mul_f32 v[58:59], v[46:47], v[46:47]
	s_waitcnt vmcnt(9)
	v_mul_f32_e32 v51, v22, v22
	v_pk_mov_b32 v[60:61], v[58:59], v[56:57] op_sel:[1,0]
	v_mov_b32_e32 v59, v57
	v_pk_add_f32 v[56:57], v[60:61], v[58:59]
	v_pk_mul_f32 v[58:59], v[44:45], v[44:45]
	v_pk_mul_f32 v[60:61], v[42:43], v[42:43]
	v_pk_add_f32 v[56:57], v[56:57], v[56:57] op_sel:[0,1] op_sel_hi:[1,0]
	v_pk_mov_b32 v[62:63], v[60:61], v[58:59] op_sel:[1,0]
	v_mov_b32_e32 v61, v59
	v_pk_add_f32 v[58:59], v[62:63], v[60:61]
	v_pk_mul_f32 v[60:61], v[40:41], v[40:41]
	v_pk_mul_f32 v[62:63], v[38:39], v[38:39]
	v_mov_b32_e32 v57, v51
	v_pk_mov_b32 v[64:65], v[62:63], v[60:61] op_sel:[1,0]
	v_mov_b32_e32 v63, v61
	v_pk_add_f32 v[60:61], v[64:65], v[62:63]
	v_pk_mul_f32 v[62:63], v[36:37], v[36:37]
	v_pk_mul_f32 v[64:65], v[34:35], v[34:35]
	v_pk_add_f32 v[60:61], v[60:61], v[60:61] op_sel:[0,1] op_sel_hi:[1,0]
	v_pk_mov_b32 v[66:67], v[64:65], v[62:63] op_sel:[1,0]
	v_mov_b32_e32 v65, v63
	v_pk_add_f32 v[62:63], v[66:67], v[64:65]
	v_mul_f32_e32 v64, v23, v23
	v_mov_b32_e32 v61, v64
	v_pk_add_f32 v[56:57], v[56:57], v[60:61]
	v_mul_f32_e32 v60, v31, v31
	v_mul_f32_e32 v65, v24, v24
	v_pk_fma_f32 v[60:61], v[30:31], v[30:31], v[60:61] op_sel_hi:[1,1,0]
	v_mul_f32_e32 v64, v33, v33
	v_mul_f32_e32 v66, v25, v25
	v_mov_b32_e32 v61, v65
	v_pk_fma_f32 v[64:65], v[32:33], v[32:33], v[64:65] op_sel_hi:[1,1,0]
	s_waitcnt vmcnt(8)
	v_mul_f32_e32 v51, v18, v18
	v_mov_b32_e32 v65, v66
	v_pk_add_f32 v[60:61], v[60:61], v[64:65]
	v_mul_f32_e32 v64, v19, v19
	v_pk_add_f32 v[56:57], v[56:57], v[60:61]
	v_pk_add_f32 v[58:59], v[58:59], v[58:59] op_sel:[0,1] op_sel_hi:[1,0]
	v_pk_add_f32 v[60:61], v[62:63], v[62:63] op_sel:[0,1] op_sel_hi:[1,0]
	v_mov_b32_e32 v59, v51
	v_mov_b32_e32 v61, v64
	v_pk_add_f32 v[58:59], v[58:59], v[60:61]
	v_mul_f32_e32 v60, v27, v27
	v_mul_f32_e32 v62, v29, v29
	v_mul_f32_e32 v65, v20, v20
	v_mul_f32_e32 v66, v21, v21
	v_pk_fma_f32 v[60:61], v[26:27], v[26:27], v[60:61] op_sel_hi:[1,1,0]
	v_pk_fma_f32 v[62:63], v[28:29], v[28:29], v[62:63] op_sel_hi:[1,1,0]
	v_mov_b32_e32 v61, v65
	v_mov_b32_e32 v63, v66
	v_pk_add_f32 v[60:61], v[60:61], v[62:63]
	s_nop 0
	v_pk_add_f32 v[58:59], v[58:59], v[60:61]
	v_mov_b32_e32 v61, v56
	v_mov_b32_e32 v60, v58
	v_mov_b32_e32 v56, v59
	v_pk_add_f32 v[56:57], v[60:61], v[56:57]
	s_nop 1
	v_add_f32_dpp v56, v56, v56 quad_perm:[1,0,3,2] row_mask:0xf bank_mask:0xf
	v_add_f32_dpp v57, v57, v57 quad_perm:[1,0,3,2] row_mask:0xf bank_mask:0xf
	s_nop 0
	v_add_f32_dpp v56, v56, v56 quad_perm:[2,3,0,1] row_mask:0xf bank_mask:0xf
	v_add_f32_dpp v57, v57, v57 quad_perm:[2,3,0,1] row_mask:0xf bank_mask:0xf
	s_nop 0
	v_add_f32_dpp v56, v56, v56 row_half_mirror row_mask:0xf bank_mask:0xf
	v_add_f32_dpp v57, v57, v57 row_half_mirror row_mask:0xf bank_mask:0xf
	s_nop 0
	v_add_f32_dpp v56, v56, v56 row_mirror row_mask:0xf bank_mask:0xf
	v_add_f32_dpp v57, v57, v57 row_mirror row_mask:0xf bank_mask:0xf
	s_nop 0
	v_mov_b32_e32 v58, v56
	v_mov_b32_e32 v59, v57
	s_nop 1
	v_permlane16_swap_b32_e32 v56, v58
	v_permlane16_swap_b32_e32 v57, v59
	v_add_f32_e32 v56, v56, v58
	v_add_f32_e32 v57, v57, v59
	v_mov_b32_e32 v58, v56
	v_mov_b32_e32 v59, v57
	s_nop 1
	v_permlane32_swap_b32_e32 v56, v58
	v_permlane32_swap_b32_e32 v57, v59
	v_add_f32_e32 v56, v56, v58
	v_add_f32_e32 v57, v57, v59
	s_nop 0
	v_pk_fma_f32 v[56:57], v[56:57], s[8:9], v[206:207] op_sel_hi:[1,0,0]
	s_nop 0
	v_mul_f32_e32 v51, 0x4b800000, v57
	v_cmp_gt_f32_e64 s[40:41], s82, v57
	v_cmp_gt_f32_e32 vcc, s82, v56
	s_nop 0
	v_cndmask_b32_e64 v51, v57, v51, s[40:41]
	v_rsq_f32_e32 v51, v51
	s_nop 0
	v_mul_f32_e32 v57, 0x45800000, v51
	v_cndmask_b32_e64 v58, v51, v57, s[40:41]
	v_mul_f32_e32 v51, 0x4b800000, v56
	v_cndmask_b32_e32 v51, v56, v51, vcc
	v_rsq_f32_e32 v51, v51
	v_pk_mul_f32 v[46:47], v[46:47], v[58:59] op_sel_hi:[1,0]
	v_pk_mul_f32 v[48:49], v[48:49], v[58:59] op_sel_hi:[1,0]
	v_pk_mul_f32 v[38:39], v[38:39], v[58:59] op_sel_hi:[1,0]
	v_mul_f32_e32 v56, 0x45800000, v51
	v_cndmask_b32_e32 v56, v51, v56, vcc
	v_pk_mul_f32 v[42:43], v[42:43], v[56:57] op_sel_hi:[1,0]
	v_pk_mul_f32 v[44:45], v[44:45], v[56:57] op_sel_hi:[1,0]
	v_pk_mul_f32 v[40:41], v[40:41], v[58:59] op_sel_hi:[1,0]
	v_pk_mul_f32 v[34:35], v[34:35], v[56:57] op_sel_hi:[1,0]
	v_pk_mul_f32 v[36:37], v[36:37], v[56:57] op_sel_hi:[1,0]
	v_pk_mul_f32 v[30:31], v[30:31], v[58:59] op_sel_hi:[1,0]
	v_pk_mul_f32 v[32:33], v[32:33], v[58:59] op_sel_hi:[1,0]
	v_pk_mul_f32 v[26:27], v[26:27], v[56:57] op_sel_hi:[1,0]
; __device__ __forceinline__ void final_phase(const Params& p) {
;     ...
;         for (int rr = 0; rr < RPW; rr += 2) {
;             f32x4* xa = (f32x4*)(p.out + (size_t)(r0 + rr) * DM) + lane; f32x4* xb = xa + DM / 4;
;             f32x4 va[4], vb[4]; float sa = 0.f, sb = 0.f;
; #pragma unroll
;             for (int j = 0; j < 4; ++j) { va[j] = __builtin_nontemporal_load(xa + 64 * j); vb[j] = __builtin_nontemporal_load(xb + 64 * j); }
; #pragma unroll
;             for (int j = 0; j < 4; ++j) { sa += (va[j][0] * va[j][0] + va[j][1] * va[j][1]) + (va[j][2] * va[j][2] + va[j][3] * va[j][3]); sb += (vb[j][0] * vb[j][0] + vb[j][1] * vb[j][1]) + (vb[j][2] * vb[j][2] + vb[j][3] * vb[j][3]); }
;             const float ra = rsqrtf(wave_sum(sa, x32a) * (1.0f / DM) + 1e-6f), rb = rsqrtf(wave_sum(sb, x32a) * (1.0f / DM) + 1e-6f);
; #pragma unroll
;             for (int j = 0; j < 4; ++j) { xa[64 * j] = (va[j] * ra) * gg[j]; xb[64 * j] = (vb[j] * rb) * gg[j]; }
	v_pk_mul_f32 v[28:29], v[28:29], v[56:57] op_sel_hi:[1,0]
	v_pk_mul_f32 v[22:23], v[22:23], v[58:59] op_sel_hi:[1,0]
	v_pk_mul_f32 v[24:25], v[24:25], v[58:59] op_sel_hi:[1,0]
	v_pk_mul_f32 v[18:19], v[18:19], v[56:57] op_sel_hi:[1,0]
	v_pk_mul_f32 v[20:21], v[20:21], v[56:57] op_sel_hi:[1,0]
	v_pk_mul_f32 v[48:49], v[4:5], v[48:49]
	v_pk_mul_f32 v[46:47], v[2:3], v[46:47]
	v_pk_mul_f32 v[44:45], v[4:5], v[44:45]
	v_pk_mul_f32 v[42:43], v[2:3], v[42:43]
	v_pk_mul_f32 v[40:41], v[8:9], v[40:41]
	v_pk_mul_f32 v[38:39], v[6:7], v[38:39]
	v_pk_mul_f32 v[36:37], v[8:9], v[36:37]
	v_pk_mul_f32 v[34:35], v[6:7], v[34:35]
	v_pk_mul_f32 v[32:33], v[12:13], v[32:33]
	v_pk_mul_f32 v[30:31], v[10:11], v[30:31]
	v_pk_mul_f32 v[28:29], v[12:13], v[28:29]
	v_pk_mul_f32 v[26:27], v[10:11], v[26:27]
	v_pk_mul_f32 v[24:25], v[16:17], v[24:25]
	v_pk_mul_f32 v[22:23], v[14:15], v[22:23]
	v_pk_mul_f32 v[20:21], v[16:17], v[20:21]
	v_pk_mul_f32 v[18:19], v[14:15], v[18:19]
	global_store_dwordx4 v[54:55], v[46:49], off offset:-4096
	global_store_dwordx4 v[54:55], v[42:45], off
	global_store_dwordx4 v[54:55], v[38:41], off offset:-3072
	global_store_dwordx4 v[54:55], v[34:37], off offset:1024
	global_store_dwordx4 v[54:55], v[30:33], off offset:-2048
	global_store_dwordx4 v[54:55], v[26:29], off offset:2048
	global_store_dwordx4 v[54:55], v[22:25], off offset:-1024
	global_store_dwordx4 v[54:55], v[18:21], off offset:3072
	v_lshl_add_u64 v[54:55], v[54:55], 0, s[6:7]
	s_add_i32 s4, s4, 2
	s_cmp_gt_u32 s4, 13
	s_waitcnt vmcnt(8)
	v_pk_mul_f32 v[56:57], v[72:73], v[72:73]
	v_pk_mul_f32 v[58:59], v[70:71], v[70:71]
	s_waitcnt vmcnt(9)
	v_mul_f32_e32 v51, v94, v94
	v_pk_mov_b32 v[60:61], v[58:59], v[56:57] op_sel:[1,0]
	v_mov_b32_e32 v59, v57
	v_pk_add_f32 v[56:57], v[60:61], v[58:59]
	v_pk_mul_f32 v[58:59], v[76:77], v[76:77]
	v_pk_mul_f32 v[60:61], v[74:75], v[74:75]
	v_pk_add_f32 v[56:57], v[56:57], v[56:57] op_sel:[0,1] op_sel_hi:[1,0]
	v_pk_mov_b32 v[62:63], v[60:61], v[58:59] op_sel:[1,0]
	v_mov_b32_e32 v61, v59
	v_pk_add_f32 v[58:59], v[62:63], v[60:61]
	v_pk_mul_f32 v[60:61], v[80:81], v[80:81]
	v_pk_mul_f32 v[62:63], v[78:79], v[78:79]
	v_mov_b32_e32 v57, v51
	v_pk_mov_b32 v[64:65], v[62:63], v[60:61] op_sel:[1,0]
	v_mov_b32_e32 v63, v61
	v_pk_add_f32 v[60:61], v[64:65], v[62:63]
	v_pk_mul_f32 v[62:63], v[84:85], v[84:85]
	v_pk_mul_f32 v[64:65], v[82:83], v[82:83]
	v_pk_add_f32 v[60:61], v[60:61], v[60:61] op_sel:[0,1] op_sel_hi:[1,0]
	v_pk_mov_b32 v[66:67], v[64:65], v[62:63] op_sel:[1,0]
	v_mov_b32_e32 v65, v63
	v_pk_add_f32 v[62:63], v[66:67], v[64:65]
	v_mul_f32_e32 v64, v95, v95
	v_mov_b32_e32 v61, v64
	v_pk_add_f32 v[56:57], v[56:57], v[60:61]
	v_mul_f32_e32 v60, v87, v87
	v_mul_f32_e32 v65, v96, v96
	v_pk_fma_f32 v[60:61], v[86:87], v[86:87], v[60:61] op_sel_hi:[1,1,0]
	v_mul_f32_e32 v64, v89, v89
	v_mul_f32_e32 v66, v97, v97
	v_mov_b32_e32 v61, v65
	v_pk_fma_f32 v[64:65], v[88:89], v[88:89], v[64:65] op_sel_hi:[1,1,0]
	s_waitcnt vmcnt(8)
; template <int X> __device__ __forceinline__ float swz_xor(float v) { return __int_as_float(__builtin_amdgcn_ds_swizzle(__float_as_int(v), 0x1f | (X << 10))); }
; __device__ __forceinline__ float xor32(float v, int x32a) { return __int_as_float(__builtin_amdgcn_ds_bpermute(x32a, __float_as_int(v))); }
; __device__ __forceinline__ float wave_sum(float v, int x32a) {
;     v += swz_xor<1>(v); v += swz_xor<2>(v); v += swz_xor<4>(v); v += swz_xor<8>(v); v += swz_xor<16>(v); v += xor32(v, x32a);
;     return v;
; __device__ __forceinline__ void final_phase(const Params& p) {
;     ...
;     for (int r0 = gw * RPW; r0 < MTOK; r0 += ngw * RPW) {
;         for (int rr = 0; rr < RPW; rr += 2) {
;             f32x4* xa = (f32x4*)(p.out + (size_t)(r0 + rr) * DM) + lane; f32x4* xb = xa + DM / 4;
;             f32x4 va[4], vb[4]; float sa = 0.f, sb = 0.f;
; #pragma unroll
;             for (int j = 0; j < 4; ++j) { va[j] = __builtin_nontemporal_load(xa + 64 * j); vb[j] = __builtin_nontemporal_load(xb + 64 * j); }
; #pragma unroll
;             for (int j = 0; j < 4; ++j) { sa += (va[j][0] * va[j][0] + va[j][1] * va[j][1]) + (va[j][2] * va[j][2] + va[j][3] * va[j][3]); sb += (vb[j][0] * vb[j][0] + vb[j][1] * vb[j][1]) + (vb[j][2] * vb[j][2] + vb[j][3] * vb[j][3]); }
;             const float ra = rsqrtf(wave_sum(sa, x32a) * (1.0f / DM) + 1e-6f), rb = rsqrtf(wave_sum(sb, x32a) * (1.0f / DM) + 1e-6f);
; #pragma unroll
;             for (int j = 0; j < 4; ++j) { xa[64 * j] = (va[j] * ra) * gg[j]; xb[64 * j] = (vb[j] * rb) * gg[j]; }
	v_mul_f32_e32 v51, v98, v98
	v_mov_b32_e32 v65, v66
	v_pk_add_f32 v[60:61], v[60:61], v[64:65]
	v_mul_f32_e32 v64, v99, v99
	v_pk_add_f32 v[56:57], v[56:57], v[60:61]
	v_pk_add_f32 v[58:59], v[58:59], v[58:59] op_sel:[0,1] op_sel_hi:[1,0]
	v_pk_add_f32 v[60:61], v[62:63], v[62:63] op_sel:[0,1] op_sel_hi:[1,0]
	v_mov_b32_e32 v59, v51
	v_mov_b32_e32 v61, v64
	v_pk_add_f32 v[58:59], v[58:59], v[60:61]
	v_mul_f32_e32 v60, v91, v91
	v_mul_f32_e32 v62, v93, v93
	v_mul_f32_e32 v65, v100, v100
	v_mul_f32_e32 v66, v101, v101
	v_pk_fma_f32 v[60:61], v[90:91], v[90:91], v[60:61] op_sel_hi:[1,1,0]
	v_pk_fma_f32 v[62:63], v[92:93], v[92:93], v[62:63] op_sel_hi:[1,1,0]
	v_mov_b32_e32 v61, v65
	v_mov_b32_e32 v63, v66
	v_pk_add_f32 v[60:61], v[60:61], v[62:63]
	s_nop 0
	v_pk_add_f32 v[58:59], v[58:59], v[60:61]
	v_mov_b32_e32 v61, v56
	v_mov_b32_e32 v60, v58
	v_mov_b32_e32 v56, v59
	v_pk_add_f32 v[56:57], v[60:61], v[56:57]
	s_nop 1
	v_add_f32_dpp v56, v56, v56 quad_perm:[1,0,3,2] row_mask:0xf bank_mask:0xf
	v_add_f32_dpp v57, v57, v57 quad_perm:[1,0,3,2] row_mask:0xf bank_mask:0xf
	s_nop 0
	v_add_f32_dpp v56, v56, v56 quad_perm:[2,3,0,1] row_mask:0xf bank_mask:0xf
	v_add_f32_dpp v57, v57, v57 quad_perm:[2,3,0,1] row_mask:0xf bank_mask:0xf
	s_nop 0
	v_add_f32_dpp v56, v56, v56 row_half_mirror row_mask:0xf bank_mask:0xf
	v_add_f32_dpp v57, v57, v57 row_half_mirror row_mask:0xf bank_mask:0xf
	s_nop 0
	v_add_f32_dpp v56, v56, v56 row_mirror row_mask:0xf bank_mask:0xf
	v_add_f32_dpp v57, v57, v57 row_mirror row_mask:0xf bank_mask:0xf
	s_nop 0
	v_mov_b32_e32 v58, v56
	v_mov_b32_e32 v59, v57
	s_nop 1
	v_permlane16_swap_b32_e32 v56, v58
	v_permlane16_swap_b32_e32 v57, v59
	v_add_f32_e32 v56, v56, v58
	v_add_f32_e32 v57, v57, v59
	v_mov_b32_e32 v58, v56
	v_mov_b32_e32 v59, v57
	s_nop 1
	v_permlane32_swap_b32_e32 v56, v58
	v_permlane32_swap_b32_e32 v57, v59
	v_add_f32_e32 v56, v56, v58
	v_add_f32_e32 v57, v57, v59
	s_nop 0
	v_pk_fma_f32 v[56:57], v[56:57], s[8:9], v[206:207] op_sel_hi:[1,0,0]
	s_nop 0
	v_mul_f32_e32 v51, 0x4b800000, v57
	v_cmp_gt_f32_e64 s[40:41], s82, v57
	v_cmp_gt_f32_e32 vcc, s82, v56
	s_nop 0
	v_cndmask_b32_e64 v51, v57, v51, s[40:41]
	v_rsq_f32_e32 v51, v51
	s_nop 0
	v_mul_f32_e32 v57, 0x45800000, v51
	v_cndmask_b32_e64 v58, v51, v57, s[40:41]
	v_mul_f32_e32 v51, 0x4b800000, v56
	v_cndmask_b32_e32 v51, v56, v51, vcc
	v_rsq_f32_e32 v51, v51
	v_pk_mul_f32 v[70:71], v[70:71], v[58:59] op_sel_hi:[1,0]
	v_pk_mul_f32 v[72:73], v[72:73], v[58:59] op_sel_hi:[1,0]
	v_pk_mul_f32 v[78:79], v[78:79], v[58:59] op_sel_hi:[1,0]
	v_mul_f32_e32 v56, 0x45800000, v51
	v_cndmask_b32_e32 v56, v51, v56, vcc
	v_pk_mul_f32 v[74:75], v[74:75], v[56:57] op_sel_hi:[1,0]
	v_pk_mul_f32 v[76:77], v[76:77], v[56:57] op_sel_hi:[1,0]
	v_pk_mul_f32 v[80:81], v[80:81], v[58:59] op_sel_hi:[1,0]
	v_pk_mul_f32 v[82:83], v[82:83], v[56:57] op_sel_hi:[1,0]
	v_pk_mul_f32 v[84:85], v[84:85], v[56:57] op_sel_hi:[1,0]
	v_pk_mul_f32 v[86:87], v[86:87], v[58:59] op_sel_hi:[1,0]
	v_pk_mul_f32 v[88:89], v[88:89], v[58:59] op_sel_hi:[1,0]
	v_pk_mul_f32 v[90:91], v[90:91], v[56:57] op_sel_hi:[1,0]
	v_pk_mul_f32 v[92:93], v[92:93], v[56:57] op_sel_hi:[1,0]
	v_pk_mul_f32 v[94:95], v[94:95], v[58:59] op_sel_hi:[1,0]
	v_pk_mul_f32 v[96:97], v[96:97], v[58:59] op_sel_hi:[1,0]
	v_pk_mul_f32 v[98:99], v[98:99], v[56:57] op_sel_hi:[1,0]
	v_pk_mul_f32 v[100:101], v[100:101], v[56:57] op_sel_hi:[1,0]
	v_pk_mul_f32 v[72:73], v[4:5], v[72:73]
	v_pk_mul_f32 v[70:71], v[2:3], v[70:71]
	v_pk_mul_f32 v[76:77], v[4:5], v[76:77]
	v_pk_mul_f32 v[74:75], v[2:3], v[74:75]
	v_pk_mul_f32 v[80:81], v[8:9], v[80:81]
	v_pk_mul_f32 v[78:79], v[6:7], v[78:79]
	v_pk_mul_f32 v[84:85], v[8:9], v[84:85]
	v_pk_mul_f32 v[82:83], v[6:7], v[82:83]
	v_pk_mul_f32 v[88:89], v[12:13], v[88:89]
	v_pk_mul_f32 v[86:87], v[10:11], v[86:87]
	v_pk_mul_f32 v[92:93], v[12:13], v[92:93]
	v_pk_mul_f32 v[90:91], v[10:11], v[90:91]
	v_pk_mul_f32 v[96:97], v[16:17], v[96:97]
	v_pk_mul_f32 v[94:95], v[14:15], v[94:95]
	v_pk_mul_f32 v[100:101], v[16:17], v[100:101]
	v_pk_mul_f32 v[98:99], v[14:15], v[98:99]
	global_store_dwordx4 v[54:55], v[70:73], off offset:-4096
	global_store_dwordx4 v[54:55], v[74:77], off
	global_store_dwordx4 v[54:55], v[78:81], off offset:-3072
	global_store_dwordx4 v[54:55], v[82:85], off offset:1024
	global_store_dwordx4 v[54:55], v[86:89], off offset:-2048
	global_store_dwordx4 v[54:55], v[90:93], off offset:2048
	global_store_dwordx4 v[54:55], v[94:97], off offset:-1024
	global_store_dwordx4 v[54:55], v[98:101], off offset:3072
	v_lshl_add_u64 v[54:55], v[54:55], 0, s[6:7]
	s_cbranch_scc0 .LBB0_30
	v_readlane_b32 s4, v254, 62
	v_readlane_b32 s5, v254, 63
	s_nop 0
	v_add_u32_e32 v50, s4, v50
	v_readlane_b32 s4, v254, 51
	v_cmp_lt_i32_e32 vcc, s2, v50
	v_readlane_b32 s5, v254, 52
	s_or_b64 s[42:43], vcc, s[42:43]
	s_nop 0
	v_lshl_add_u64 v[52:53], v[52:53], 0, s[4:5]
	s_andn2_b64 exec, exec, s[42:43]
	s_cbranch_execnz .LBB0_29

; __device__ __forceinline__ unsigned pk_bf16(float lo, float hi) { const f32x2 v = {lo, hi}; const bf16v2 b = __builtin_convertvector(v, bf16v2); return __builtin_bit_cast(unsigned, b); }
; template <int X> __device__ __forceinline__ float swz_xor(float v) { return __int_as_float(__builtin_amdgcn_ds_swizzle(__float_as_int(v), 0x1f | (X << 10))); }
; __device__ __forceinline__ float xor32(float v, int x32a) { return __int_as_float(__builtin_amdgcn_ds_bpermute(x32a, __float_as_int(v))); }
; __device__ __forceinline__ float wave_sum(float v, int x32a) {
;     v += swz_xor<1>(v); v += swz_xor<2>(v); v += swz_xor<4>(v); v += swz_xor<8>(v); v += swz_xor<16>(v); v += xor32(v, x32a);
;     return v;
; __device__ __forceinline__ void norm_phase(const Params& p, int layer) {
;     ...
;         for (int rr = 0; rr < RPW; rr += 2) {
;             const int row = r0 + rr;
;             const f32x4* xa = (const f32x4*)(src + (size_t)row * DM) + lane; const f32x4* xb = xa + DM / 4;
;             f32x4 va[4], vb[4]; float sa = 0.f, sb = 0.f;
; #pragma unroll
;             for (int j = 0; j < 4; ++j) { va[j] = __builtin_nontemporal_load(xa + 64 * j); vb[j] = __builtin_nontemporal_load(xb + 64 * j); }
; #pragma unroll
;             for (int j = 0; j < 4; ++j) { sa += (va[j][0] * va[j][0] + va[j][1] * va[j][1]) + (va[j][2] * va[j][2] + va[j][3] * va[j][3]); sb += (vb[j][0] * vb[j][0] + vb[j][1] * vb[j][1]) + (vb[j][2] * vb[j][2] + vb[j][3] * vb[j][3]); }
;             const float ra = rsqrtf(wave_sum(sa, x32a) * (1.0f / DM) + 1e-6f), rb = rsqrtf(wave_sum(sb, x32a) * (1.0f / DM) + 1e-6f);
; #pragma unroll
;             for (int j = 0; j < 4; ++j) { const int col = 4 * lane + 256 * j;
;                 const f32x4 ya = (va[j] * ra) * gs[j] + sh[j], yb = (vb[j] * rb) * gs[j] + sh[j];
;                 u32x2 wa, wb; wa.x = pk_bf16(ya[0], ya[1]); wa.y = pk_bf16(ya[2], ya[3]); wb.x = pk_bf16(yb[0], yb[1]); wb.y = pk_bf16(yb[2], yb[3]);
;                 *(u32x2*)(H + (size_t)row * DM + col) = wa; *(u32x2*)(H + (size_t)(row + 1) * DM + col) = wb; }
.LBB0_415:
	global_load_dwordx4 v[56:59], v[54:55], off offset:-4096 nt
	global_load_dwordx4 v[60:63], v[54:55], off nt
	global_load_dwordx4 v[64:67], v[54:55], off offset:-3072 nt
	global_load_dwordx4 v[70:73], v[54:55], off offset:1024 nt
	global_load_dwordx4 v[102:105], v[54:55], off offset:-2048 nt
	global_load_dwordx4 v[106:109], v[54:55], off offset:-1024 nt
	global_load_dwordx4 v[110:113], v[54:55], off offset:2048 nt
	global_load_dwordx4 v[114:117], v[54:55], off offset:3072 nt
	v_lshl_add_u64 v[150:151], v[54:55], 0, s[6:7]
	global_load_dwordx4 v[118:121], v[150:151], off offset:-4096 nt
	global_load_dwordx4 v[122:125], v[150:151], off nt
	global_load_dwordx4 v[126:129], v[150:151], off offset:-3072 nt
	global_load_dwordx4 v[130:133], v[150:151], off offset:1024 nt
	global_load_dwordx4 v[134:137], v[150:151], off offset:-2048 nt
	global_load_dwordx4 v[138:141], v[150:151], off offset:-1024 nt
	global_load_dwordx4 v[142:145], v[150:151], off offset:2048 nt
	global_load_dwordx4 v[146:149], v[150:151], off offset:3072 nt
	s_waitcnt vmcnt(15)
	v_pk_mul_f32 v[68:69], v[58:59], v[58:59]
	v_pk_mul_f32 v[74:75], v[56:57], v[56:57]
	s_waitcnt vmcnt(14)
	v_pk_mul_f32 v[76:77], v[62:63], v[62:63]
	v_pk_mov_b32 v[78:79], v[74:75], v[68:69] op_sel:[1,0]
	v_mov_b32_e32 v75, v69
	v_pk_mul_f32 v[68:69], v[60:61], v[60:61]
	s_waitcnt vmcnt(13)
	v_pk_mul_f32 v[82:83], v[64:65], v[64:65]
	v_pk_mov_b32 v[80:81], v[68:69], v[76:77] op_sel:[1,0]
	v_mov_b32_e32 v69, v77
	v_pk_mul_f32 v[76:77], v[66:67], v[66:67]
	s_waitcnt vmcnt(12)
	v_pk_mul_f32 v[86:87], v[70:71], v[70:71]
	v_pk_mov_b32 v[84:85], v[82:83], v[76:77] op_sel:[1,0]
	v_mov_b32_e32 v83, v77
	v_pk_mul_f32 v[76:77], v[72:73], v[72:73]
	v_pk_add_f32 v[90:91], v[78:79], v[74:75]
	v_pk_mov_b32 v[88:89], v[86:87], v[76:77] op_sel:[1,0]
	v_mov_b32_e32 v87, v77
	v_pk_add_f32 v[68:69], v[80:81], v[68:69]
	v_pk_add_f32 v[92:93], v[84:85], v[82:83]
	v_pk_add_f32 v[94:95], v[88:89], v[86:87]
	v_pk_add_f32 v[90:91], v[90:91], v[90:91] op_sel:[0,1] op_sel_hi:[1,0]
	v_pk_add_f32 v[92:93], v[92:93], v[92:93] op_sel:[0,1] op_sel_hi:[1,0]
	v_pk_add_f32 v[68:69], v[68:69], v[68:69] op_sel:[0,1] op_sel_hi:[1,0]
	s_waitcnt vmcnt(11)
	v_mul_f32_e32 v82, v103, v103
	v_mul_f32_e32 v84, v105, v105
	v_pk_fma_f32 v[82:83], v[102:103], v[102:103], v[82:83] op_sel_hi:[1,1,0]
	v_pk_fma_f32 v[84:85], v[104:105], v[104:105], v[84:85] op_sel_hi:[1,1,0]
	s_waitcnt vmcnt(10)
	v_mul_f32_e32 v83, v108, v108
	v_mul_f32_e32 v85, v109, v109
	v_pk_add_f32 v[96:97], v[82:83], v[84:85]
	v_mul_f32_e32 v91, v106, v106
	v_mul_f32_e32 v93, v107, v107
	v_pk_add_f32 v[90:91], v[90:91], v[92:93]
	v_pk_add_f32 v[92:93], v[94:95], v[94:95] op_sel:[0,1] op_sel_hi:[1,0]
	v_pk_add_f32 v[90:91], v[90:91], v[96:97]
	v_lshl_add_u64 v[54:55], v[54:55], 0, s[6:7]
	s_waitcnt vmcnt(9)
	v_mul_f32_e32 v98, v111, v111
	v_mul_f32_e32 v100, v113, v113
	v_pk_fma_f32 v[98:99], v[110:111], v[110:111], v[98:99] op_sel_hi:[1,1,0]
	v_pk_fma_f32 v[100:101], v[112:113], v[112:113], v[100:101] op_sel_hi:[1,1,0]
	s_waitcnt vmcnt(8)
	v_mul_f32_e32 v99, v116, v116
	v_mul_f32_e32 v101, v117, v117
	v_mul_f32_e32 v69, v114, v114
	v_mul_f32_e32 v93, v115, v115
	v_pk_add_f32 v[98:99], v[98:99], v[100:101]
	v_pk_add_f32 v[68:69], v[68:69], v[92:93]
	v_mov_b32_e32 v93, v90
	v_pk_add_f32 v[68:69], v[68:69], v[98:99]
	s_nop 0
	v_mov_b32_e32 v92, v68
	v_mov_b32_e32 v90, v69
	v_pk_add_f32 v[68:69], v[92:93], v[90:91]
	s_nop 1
	v_add_f32_dpp v68, v68, v68 quad_perm:[1,0,3,2] row_mask:0xf bank_mask:0xf
	v_add_f32_dpp v69, v69, v69 quad_perm:[1,0,3,2] row_mask:0xf bank_mask:0xf
	s_nop 0
	v_add_f32_dpp v68, v68, v68 quad_perm:[2,3,0,1] row_mask:0xf bank_mask:0xf
	v_add_f32_dpp v69, v69, v69 quad_perm:[2,3,0,1] row_mask:0xf bank_mask:0xf
	s_nop 0
	v_add_f32_dpp v68, v68, v68 row_half_mirror row_mask:0xf bank_mask:0xf
	v_add_f32_dpp v69, v69, v69 row_half_mirror row_mask:0xf bank_mask:0xf
	s_nop 0
	v_add_f32_dpp v68, v68, v68 row_mirror row_mask:0xf bank_mask:0xf
	v_add_f32_dpp v69, v69, v69 row_mirror row_mask:0xf bank_mask:0xf
	s_nop 0
	v_mov_b32_e32 v90, v68
	v_mov_b32_e32 v91, v69
	s_nop 1
	v_permlane16_swap_b32_e32 v68, v90
	v_permlane16_swap_b32_e32 v69, v91
	v_add_f32_e32 v68, v68, v90
	v_add_f32_e32 v69, v69, v91
	v_mov_b32_e32 v90, v68
	v_mov_b32_e32 v91, v69
	s_nop 1
	v_permlane32_swap_b32_e32 v68, v90
	v_permlane32_swap_b32_e32 v69, v91
	v_add_f32_e32 v68, v68, v90
	v_add_f32_e32 v69, v69, v91
	s_nop 0
	v_pk_fma_f32 v[90:91], v[68:69], s[8:9], v[206:207] op_sel_hi:[1,0,0]
	s_nop 0
	v_mul_f32_e32 v19, 0x4b800000, v91
	v_cmp_gt_f32_e32 vcc, s82, v91
	s_nop 1
	v_cndmask_b32_e32 v19, v91, v19, vcc
	v_rsq_f32_e32 v19, v19
	s_nop 0
	v_mul_f32_e32 v29, 0x45800000, v19
	v_cndmask_b32_e32 v68, v19, v29, vcc
	v_mul_f32_e32 v19, 0x4b800000, v90
	v_cmp_gt_f32_e32 vcc, s82, v90
	v_pk_mul_f32 v[56:57], v[56:57], v[68:69] op_sel_hi:[1,0]
	v_pk_mul_f32 v[58:59], v[58:59], v[68:69] op_sel_hi:[1,0]
	v_cndmask_b32_e32 v19, v90, v19, vcc
	v_rsq_f32_e32 v19, v19
	v_pk_mul_f32 v[94:95], v[102:103], v[68:69] op_sel_hi:[1,0]
	v_pk_fma_f32 v[58:59], v[36:37], v[58:59], v[4:5]
	v_pk_fma_f32 v[56:57], v[38:39], v[56:57], v[2:3]
	v_mul_f32_e32 v29, 0x45800000, v19
	v_cndmask_b32_e32 v74, v19, v29, vcc
	v_pk_mul_f32 v[60:61], v[60:61], v[74:75] op_sel_hi:[1,0]
	v_pk_mul_f32 v[62:63], v[62:63], v[74:75] op_sel_hi:[1,0]
	v_pk_mul_f32 v[64:65], v[64:65], v[68:69] op_sel_hi:[1,0]
	v_pk_mul_f32 v[92:93], v[66:67], v[68:69] op_sel_hi:[1,0]
	v_cvt_pk_bf16_f32 v56, v56, v57
	v_cvt_pk_bf16_f32 v57, v58, v59
	v_pk_fma_f32 v[62:63], v[36:37], v[62:63], v[4:5]
	v_pk_fma_f32 v[58:59], v[38:39], v[60:61], v[2:3]
; __device__ __forceinline__ unsigned pk_bf16(float lo, float hi) { const f32x2 v = {lo, hi}; const bf16v2 b = __builtin_convertvector(v, bf16v2); return __builtin_bit_cast(unsigned, b); }
; __device__ __forceinline__ void norm_phase(const Params& p, int layer) {
;     ...
;         for (int rr = 0; rr < RPW; rr += 2) {
;             const int row = r0 + rr;
;             const f32x4* xa = (const f32x4*)(src + (size_t)row * DM) + lane; const f32x4* xb = xa + DM / 4;
;             f32x4 va[4], vb[4]; float sa = 0.f, sb = 0.f;
; #pragma unroll
;             for (int j = 0; j < 4; ++j) { va[j] = __builtin_nontemporal_load(xa + 64 * j); vb[j] = __builtin_nontemporal_load(xb + 64 * j); }
; #pragma unroll
;             for (int j = 0; j < 4; ++j) { sa += (va[j][0] * va[j][0] + va[j][1] * va[j][1]) + (va[j][2] * va[j][2] + va[j][3] * va[j][3]); sb += (vb[j][0] * vb[j][0] + vb[j][1] * vb[j][1]) + (vb[j][2] * vb[j][2] + vb[j][3] * vb[j][3]); }
;             const float ra = rsqrtf(wave_sum(sa, x32a) * (1.0f / DM) + 1e-6f), rb = rsqrtf(wave_sum(sb, x32a) * (1.0f / DM) + 1e-6f);
; #pragma unroll
;             for (int j = 0; j < 4; ++j) { const int col = 4 * lane + 256 * j;
;                 const f32x4 ya = (va[j] * ra) * gs[j] + sh[j], yb = (vb[j] * rb) * gs[j] + sh[j];
;                 u32x2 wa, wb; wa.x = pk_bf16(ya[0], ya[1]); wa.y = pk_bf16(ya[2], ya[3]); wb.x = pk_bf16(yb[0], yb[1]); wb.y = pk_bf16(yb[2], yb[3]);
;                 *(u32x2*)(H + (size_t)row * DM + col) = wa; *(u32x2*)(H + (size_t)(row + 1) * DM + col) = wb; }
	v_pk_mul_f32 v[96:97], v[104:105], v[68:69] op_sel_hi:[1,0]
	v_pk_mul_f32 v[66:67], v[106:107], v[68:69] op_sel_hi:[1,0]
	v_pk_mul_f32 v[68:69], v[108:109], v[68:69] op_sel_hi:[1,0]
	v_pk_mul_f32 v[78:79], v[70:71], v[74:75] op_sel_hi:[1,0]
	v_pk_mul_f32 v[80:81], v[72:73], v[74:75] op_sel_hi:[1,0]
	v_cvt_pk_bf16_f32 v58, v58, v59
	v_cvt_pk_bf16_f32 v59, v62, v63
	v_pk_fma_f32 v[62:63], v[40:41], v[92:93], v[12:13]
	v_pk_fma_f32 v[60:61], v[42:43], v[64:65], v[10:11]
	v_pk_fma_f32 v[64:65], v[40:41], v[80:81], v[12:13]
	v_cvt_pk_bf16_f32 v60, v60, v61
	v_cvt_pk_bf16_f32 v61, v62, v63
	v_pk_fma_f32 v[62:63], v[42:43], v[78:79], v[10:11]
	v_pk_fma_f32 v[78:79], v[44:45], v[96:97], v[16:17]
	v_cvt_pk_bf16_f32 v62, v62, v63
	v_cvt_pk_bf16_f32 v63, v64, v65
	v_pk_fma_f32 v[64:65], v[46:47], v[94:95], v[14:15]
	v_pk_mul_f32 v[72:73], v[110:111], v[74:75] op_sel_hi:[1,0]
	v_cvt_pk_bf16_f32 v64, v64, v65
	v_cvt_pk_bf16_f32 v65, v78, v79
	v_add3_u32 v78, v18, s4, 3
	v_pk_mul_f32 v[76:77], v[112:113], v[74:75] op_sel_hi:[1,0]
	v_pk_mul_f32 v[70:71], v[114:115], v[74:75] op_sel_hi:[1,0]
	v_pk_mul_f32 v[74:75], v[116:117], v[74:75] op_sel_hi:[1,0]
	v_ashrrev_i32_e32 v79, 31, v78
	s_add_i32 s4, s4, 2
	v_lshlrev_b64 v[78:79], 11, v[78:79]
	v_pk_fma_f32 v[76:77], v[44:45], v[76:77], v[16:17]
	v_pk_fma_f32 v[72:73], v[46:47], v[72:73], v[14:15]
	v_pk_fma_f32 v[68:69], v[48:49], v[68:69], v[8:9]
	v_pk_fma_f32 v[66:67], v[50:51], v[66:67], v[6:7]
	v_pk_fma_f32 v[74:75], v[48:49], v[74:75], v[8:9]
	v_pk_fma_f32 v[70:71], v[50:51], v[70:71], v[6:7]
	s_cmp_gt_u32 s4, 13
	v_lshl_add_u64 v[78:79], v[22:23], 0, v[78:79]
	v_cvt_pk_bf16_f32 v72, v72, v73
	v_cvt_pk_bf16_f32 v73, v76, v77
	v_cvt_pk_bf16_f32 v66, v66, v67
	v_cvt_pk_bf16_f32 v67, v68, v69
	v_cvt_pk_bf16_f32 v68, v70, v71
	v_cvt_pk_bf16_f32 v69, v74, v75
	global_store_dwordx2 v[52:53], v[56:57], off offset:-1024
	global_store_dwordx2 v[78:79], v[58:59], off
	global_store_dwordx2 v[52:53], v[60:61], off offset:-512
	global_store_dwordx2 v[78:79], v[62:63], off offset:512
	global_store_dwordx2 v[52:53], v[64:65], off
	global_store_dwordx2 v[78:79], v[72:73], off offset:1024
	global_store_dwordx2 v[52:53], v[66:67], off offset:512
	global_store_dwordx2 v[78:79], v[68:69], off offset:1536
	v_lshl_add_u64 v[52:53], v[52:53], 0, s[98:99]
	s_waitcnt vmcnt(15)
	v_pk_mul_f32 v[68:69], v[120:121], v[120:121]
	v_pk_mul_f32 v[74:75], v[118:119], v[118:119]
	s_waitcnt vmcnt(14)
	v_pk_mul_f32 v[76:77], v[124:125], v[124:125]
	v_pk_mov_b32 v[78:79], v[74:75], v[68:69] op_sel:[1,0]
	v_mov_b32_e32 v75, v69
	v_pk_mul_f32 v[68:69], v[122:123], v[122:123]
	s_waitcnt vmcnt(13)
	v_pk_mul_f32 v[82:83], v[126:127], v[126:127]
	v_pk_mov_b32 v[80:81], v[68:69], v[76:77] op_sel:[1,0]
	v_mov_b32_e32 v69, v77
	v_pk_mul_f32 v[76:77], v[128:129], v[128:129]
	s_waitcnt vmcnt(12)
	v_pk_mul_f32 v[86:87], v[130:131], v[130:131]
	v_pk_mov_b32 v[84:85], v[82:83], v[76:77] op_sel:[1,0]
	v_mov_b32_e32 v83, v77
	v_pk_mul_f32 v[76:77], v[132:133], v[132:133]
	v_pk_add_f32 v[90:91], v[78:79], v[74:75]
	v_pk_mov_b32 v[88:89], v[86:87], v[76:77] op_sel:[1,0]
	v_mov_b32_e32 v87, v77
	v_pk_add_f32 v[68:69], v[80:81], v[68:69]
	v_pk_add_f32 v[92:93], v[84:85], v[82:83]
	v_pk_add_f32 v[94:95], v[88:89], v[86:87]
	v_pk_add_f32 v[90:91], v[90:91], v[90:91] op_sel:[0,1] op_sel_hi:[1,0]
	v_pk_add_f32 v[92:93], v[92:93], v[92:93] op_sel:[0,1] op_sel_hi:[1,0]
	v_pk_add_f32 v[68:69], v[68:69], v[68:69] op_sel:[0,1] op_sel_hi:[1,0]
	s_waitcnt vmcnt(11)
	v_mul_f32_e32 v82, v135, v135
	v_mul_f32_e32 v84, v137, v137
	v_pk_fma_f32 v[82:83], v[134:135], v[134:135], v[82:83] op_sel_hi:[1,1,0]
	v_pk_fma_f32 v[84:85], v[136:137], v[136:137], v[84:85] op_sel_hi:[1,1,0]
	s_waitcnt vmcnt(10)
	v_mul_f32_e32 v83, v140, v140
	v_mul_f32_e32 v85, v141, v141
	v_pk_add_f32 v[96:97], v[82:83], v[84:85]
	v_mul_f32_e32 v91, v138, v138
	v_mul_f32_e32 v93, v139, v139
	v_pk_add_f32 v[90:91], v[90:91], v[92:93]
	v_pk_add_f32 v[92:93], v[94:95], v[94:95] op_sel:[0,1] op_sel_hi:[1,0]
	v_pk_add_f32 v[90:91], v[90:91], v[96:97]
	v_lshl_add_u64 v[54:55], v[54:55], 0, s[6:7]
	s_waitcnt vmcnt(9)
	v_mul_f32_e32 v98, v143, v143
	v_mul_f32_e32 v100, v145, v145
	v_pk_fma_f32 v[98:99], v[142:143], v[142:143], v[98:99] op_sel_hi:[1,1,0]
	v_pk_fma_f32 v[100:101], v[144:145], v[144:145], v[100:101] op_sel_hi:[1,1,0]
	s_waitcnt vmcnt(8)
; __device__ __forceinline__ unsigned pk_bf16(float lo, float hi) { const f32x2 v = {lo, hi}; const bf16v2 b = __builtin_convertvector(v, bf16v2); return __builtin_bit_cast(unsigned, b); }
; template <int X> __device__ __forceinline__ float swz_xor(float v) { return __int_as_float(__builtin_amdgcn_ds_swizzle(__float_as_int(v), 0x1f | (X << 10))); }
; __device__ __forceinline__ float xor32(float v, int x32a) { return __int_as_float(__builtin_amdgcn_ds_bpermute(x32a, __float_as_int(v))); }
; __device__ __forceinline__ float wave_sum(float v, int x32a) {
;     v += swz_xor<1>(v); v += swz_xor<2>(v); v += swz_xor<4>(v); v += swz_xor<8>(v); v += swz_xor<16>(v); v += xor32(v, x32a);
;     return v;
; __device__ __forceinline__ void norm_phase(const Params& p, int layer) {
;     ...
;         for (int rr = 0; rr < RPW; rr += 2) {
;             const int row = r0 + rr;
;             const f32x4* xa = (const f32x4*)(src + (size_t)row * DM) + lane; const f32x4* xb = xa + DM / 4;
;             f32x4 va[4], vb[4]; float sa = 0.f, sb = 0.f;
; #pragma unroll
;             for (int j = 0; j < 4; ++j) { va[j] = __builtin_nontemporal_load(xa + 64 * j); vb[j] = __builtin_nontemporal_load(xb + 64 * j); }
; #pragma unroll
;             for (int j = 0; j < 4; ++j) { sa += (va[j][0] * va[j][0] + va[j][1] * va[j][1]) + (va[j][2] * va[j][2] + va[j][3] * va[j][3]); sb += (vb[j][0] * vb[j][0] + vb[j][1] * vb[j][1]) + (vb[j][2] * vb[j][2] + vb[j][3] * vb[j][3]); }
;             const float ra = rsqrtf(wave_sum(sa, x32a) * (1.0f / DM) + 1e-6f), rb = rsqrtf(wave_sum(sb, x32a) * (1.0f / DM) + 1e-6f);
; #pragma unroll
;             for (int j = 0; j < 4; ++j) { const int col = 4 * lane + 256 * j;
;                 const f32x4 ya = (va[j] * ra) * gs[j] + sh[j], yb = (vb[j] * rb) * gs[j] + sh[j];
;                 u32x2 wa, wb; wa.x = pk_bf16(ya[0], ya[1]); wa.y = pk_bf16(ya[2], ya[3]); wb.x = pk_bf16(yb[0], yb[1]); wb.y = pk_bf16(yb[2], yb[3]);
;                 *(u32x2*)(H + (size_t)row * DM + col) = wa; *(u32x2*)(H + (size_t)(row + 1) * DM + col) = wb; }
;         }
;     }
	v_mul_f32_e32 v99, v148, v148
	v_mul_f32_e32 v101, v149, v149
	v_mul_f32_e32 v69, v146, v146
	v_mul_f32_e32 v93, v147, v147
	v_pk_add_f32 v[98:99], v[98:99], v[100:101]
	v_pk_add_f32 v[68:69], v[68:69], v[92:93]
	v_mov_b32_e32 v93, v90
	v_pk_add_f32 v[68:69], v[68:69], v[98:99]
	s_nop 0
	v_mov_b32_e32 v92, v68
	v_mov_b32_e32 v90, v69
	v_pk_add_f32 v[68:69], v[92:93], v[90:91]
	s_nop 1
	v_add_f32_dpp v68, v68, v68 quad_perm:[1,0,3,2] row_mask:0xf bank_mask:0xf
	v_add_f32_dpp v69, v69, v69 quad_perm:[1,0,3,2] row_mask:0xf bank_mask:0xf
	s_nop 0
	v_add_f32_dpp v68, v68, v68 quad_perm:[2,3,0,1] row_mask:0xf bank_mask:0xf
	v_add_f32_dpp v69, v69, v69 quad_perm:[2,3,0,1] row_mask:0xf bank_mask:0xf
	s_nop 0
	v_add_f32_dpp v68, v68, v68 row_half_mirror row_mask:0xf bank_mask:0xf
	v_add_f32_dpp v69, v69, v69 row_half_mirror row_mask:0xf bank_mask:0xf
	s_nop 0
	v_add_f32_dpp v68, v68, v68 row_mirror row_mask:0xf bank_mask:0xf
	v_add_f32_dpp v69, v69, v69 row_mirror row_mask:0xf bank_mask:0xf
	s_nop 0
	v_mov_b32_e32 v90, v68
	v_mov_b32_e32 v91, v69
	s_nop 1
	v_permlane16_swap_b32_e32 v68, v90
	v_permlane16_swap_b32_e32 v69, v91
	v_add_f32_e32 v68, v68, v90
	v_add_f32_e32 v69, v69, v91
	v_mov_b32_e32 v90, v68
	v_mov_b32_e32 v91, v69
	s_nop 1
	v_permlane32_swap_b32_e32 v68, v90
	v_permlane32_swap_b32_e32 v69, v91
	v_add_f32_e32 v68, v68, v90
	v_add_f32_e32 v69, v69, v91
	s_nop 0
	v_pk_fma_f32 v[90:91], v[68:69], s[8:9], v[206:207] op_sel_hi:[1,0,0]
	s_nop 0
	v_mul_f32_e32 v19, 0x4b800000, v91
	v_cmp_gt_f32_e32 vcc, s82, v91
	s_nop 1
	v_cndmask_b32_e32 v19, v91, v19, vcc
	v_rsq_f32_e32 v19, v19
	s_nop 0
	v_mul_f32_e32 v29, 0x45800000, v19
	v_cndmask_b32_e32 v68, v19, v29, vcc
	v_mul_f32_e32 v19, 0x4b800000, v90
	v_cmp_gt_f32_e32 vcc, s82, v90
	v_pk_mul_f32 v[118:119], v[118:119], v[68:69] op_sel_hi:[1,0]
	v_pk_mul_f32 v[120:121], v[120:121], v[68:69] op_sel_hi:[1,0]
	v_cndmask_b32_e32 v19, v90, v19, vcc
	v_rsq_f32_e32 v19, v19
	v_pk_mul_f32 v[94:95], v[134:135], v[68:69] op_sel_hi:[1,0]
	v_pk_fma_f32 v[120:121], v[36:37], v[120:121], v[4:5]
	v_pk_fma_f32 v[118:119], v[38:39], v[118:119], v[2:3]
	v_mul_f32_e32 v29, 0x45800000, v19
	v_cndmask_b32_e32 v74, v19, v29, vcc
	v_pk_mul_f32 v[122:123], v[122:123], v[74:75] op_sel_hi:[1,0]
	v_pk_mul_f32 v[124:125], v[124:125], v[74:75] op_sel_hi:[1,0]
	v_pk_mul_f32 v[126:127], v[126:127], v[68:69] op_sel_hi:[1,0]
	v_pk_mul_f32 v[92:93], v[128:129], v[68:69] op_sel_hi:[1,0]
	v_cvt_pk_bf16_f32 v118, v118, v119
	v_cvt_pk_bf16_f32 v119, v120, v121
	v_pk_fma_f32 v[124:125], v[36:37], v[124:125], v[4:5]
	v_pk_fma_f32 v[120:121], v[38:39], v[122:123], v[2:3]
	v_pk_mul_f32 v[96:97], v[136:137], v[68:69] op_sel_hi:[1,0]
	v_pk_mul_f32 v[128:129], v[138:139], v[68:69] op_sel_hi:[1,0]
	v_pk_mul_f32 v[68:69], v[140:141], v[68:69] op_sel_hi:[1,0]
	v_pk_mul_f32 v[78:79], v[130:131], v[74:75] op_sel_hi:[1,0]
	v_pk_mul_f32 v[80:81], v[132:133], v[74:75] op_sel_hi:[1,0]
	v_cvt_pk_bf16_f32 v120, v120, v121
	v_cvt_pk_bf16_f32 v121, v124, v125
	v_pk_fma_f32 v[124:125], v[40:41], v[92:93], v[12:13]
	v_pk_fma_f32 v[122:123], v[42:43], v[126:127], v[10:11]
	v_pk_fma_f32 v[126:127], v[40:41], v[80:81], v[12:13]
	v_cvt_pk_bf16_f32 v122, v122, v123
	v_cvt_pk_bf16_f32 v123, v124, v125
	v_pk_fma_f32 v[124:125], v[42:43], v[78:79], v[10:11]
	v_pk_fma_f32 v[78:79], v[44:45], v[96:97], v[16:17]
	v_cvt_pk_bf16_f32 v124, v124, v125
	v_cvt_pk_bf16_f32 v125, v126, v127
	v_pk_fma_f32 v[126:127], v[46:47], v[94:95], v[14:15]
	v_pk_mul_f32 v[132:133], v[142:143], v[74:75] op_sel_hi:[1,0]
	v_cvt_pk_bf16_f32 v126, v126, v127
	v_cvt_pk_bf16_f32 v127, v78, v79
	v_add3_u32 v78, v18, s4, 3
	v_pk_mul_f32 v[76:77], v[144:145], v[74:75] op_sel_hi:[1,0]
	v_pk_mul_f32 v[130:131], v[146:147], v[74:75] op_sel_hi:[1,0]
	v_pk_mul_f32 v[74:75], v[148:149], v[74:75] op_sel_hi:[1,0]
	v_ashrrev_i32_e32 v79, 31, v78
	s_add_i32 s4, s4, 2
	v_lshlrev_b64 v[78:79], 11, v[78:79]
	v_pk_fma_f32 v[76:77], v[44:45], v[76:77], v[16:17]
	v_pk_fma_f32 v[132:133], v[46:47], v[132:133], v[14:15]
	v_pk_fma_f32 v[68:69], v[48:49], v[68:69], v[8:9]
	v_pk_fma_f32 v[128:129], v[50:51], v[128:129], v[6:7]
	v_pk_fma_f32 v[74:75], v[48:49], v[74:75], v[8:9]
	v_pk_fma_f32 v[130:131], v[50:51], v[130:131], v[6:7]
	s_cmp_gt_u32 s4, 13
	v_lshl_add_u64 v[78:79], v[22:23], 0, v[78:79]
	v_cvt_pk_bf16_f32 v132, v132, v133
	v_cvt_pk_bf16_f32 v133, v76, v77
	v_cvt_pk_bf16_f32 v128, v128, v129
	v_cvt_pk_bf16_f32 v129, v68, v69
	v_cvt_pk_bf16_f32 v68, v130, v131
	v_cvt_pk_bf16_f32 v69, v74, v75
	global_store_dwordx2 v[52:53], v[118:119], off offset:-1024
	global_store_dwordx2 v[78:79], v[120:121], off
	global_store_dwordx2 v[52:53], v[122:123], off offset:-512
	global_store_dwordx2 v[78:79], v[124:125], off offset:512
	global_store_dwordx2 v[52:53], v[126:127], off
	global_store_dwordx2 v[78:79], v[132:133], off offset:1024
	global_store_dwordx2 v[52:53], v[128:129], off offset:512
	global_store_dwordx2 v[78:79], v[68:69], off offset:1536
	v_lshl_add_u64 v[52:53], v[52:53], 0, s[98:99]
	s_cbranch_scc0 .LBB0_415
	v_readlane_b32 s4, v254, 62
	v_readlane_b32 s5, v254, 63
	s_nop 0
	v_add_u32_e32 v18, s4, v18
	v_readlane_b32 s4, v254, 51
	v_readlane_b32 s5, v254, 52
	v_cmp_lt_i32_e32 vcc, s2, v18
	s_or_b64 s[40:41], vcc, s[40:41]
	v_lshl_add_u64 v[24:25], v[24:25], 0, s[4:5]
	v_readlane_b32 s4, v255, 0
	v_readlane_b32 s5, v255, 1
	s_nop 1
	v_lshl_add_u64 v[26:27], v[26:27], 0, s[4:5]
	s_andn2_b64 exec, exec, s[40:41]
	s_cbranch_execnz .LBB0_414
